# kept configuration + the local barrier waits for its L1 invalidate to complete before releasing the workgroup (acquire side as strict as the full barrier)
# baseline (speedup 1.0000x reference)
; __device__ __forceinline__ unsigned xb_ld(unsigned* p)              { return __hip_atomic_load(p, __ATOMIC_RELAXED, __HIP_MEMORY_SCOPE_AGENT); }
; #define XB_SPIN(cond, bar) do { unsigned _sp = 0; while (cond) { __builtin_amdgcn_s_sleep(1); \
;     if ((++_sp & 255u) == 0u) { if (xb_ld(&(bar)[XB_TMO])) break; if (_sp > XB_SPIN_CAP) { atomicAdd(&(bar)[XB_TMO], 1u); break; } } } } while (0)
; __device__ __forceinline__ void xcd_barrier(const XcdBarrier& b) {
;     ...
;             XB_SPIN(xb_ld(&bar[XB_XGEN(b.x)]) == gen, bar);
;             __builtin_amdgcn_fence(__ATOMIC_ACQUIRE, "agent");
;             asm volatile("s_waitcnt vmcnt(0)" ::: "memory");
;         }
;     }
;     __syncthreads();
cvx_done:
	buffer_inv sc0
	s_waitcnt vmcnt(0)
	s_branch .LBB0_486
